# attention: v_permlane32_swap cross-half exchange instead of 4 ds_bpermute + selects per key tile (no LDS round trip on the tile's dependency chain)
# speedup vs baseline: 1.0018x; 1.0018x over previous
.LBB0_651:
	s_max_i32 s0, s14, 0
	s_mov_b32 s6, s14
	s_add_i32 s14, s0, -1
	s_lshl_b32 s0, s14, 5
	s_add_i32 s0, s23, s0
	s_cmp_gt_i32 s6, 0
	s_waitcnt vmcnt(0)
	s_cselect_b32 s0, s0, 0x8002
	s_waitcnt lgkmcnt(0)
	v_or_b32_e32 v2, s0, v135
	v_ashrrev_i32_e32 v3, 31, v2
	v_lshlrev_b64 v[2:3], 11, v[2:3]
	ds_write_b128 v167, v[108:111]
	ds_write_b128 v167, v[104:107] offset:144
	ds_write_b128 v167, v[100:103] offset:288
	ds_write_b128 v167, v[96:99] offset:432
	ds_write_b128 v168, v[92:95] offset:4608
	ds_write_b128 v168, v[88:91] offset:4800
	ds_write_b128 v168, v[84:87] offset:4992
	ds_write_b128 v168, v[80:83] offset:5184
	v_lshl_or_b32 v2, v158, 1, v2
	v_lshl_add_u64 v[4:5], s[24:25], 0, v[2:3]
	v_lshl_add_u64 v[2:3], s[26:27], 0, v[2:3]
	global_load_dwordx4 v[108:111], v[4:5], off offset:-4096
	global_load_dwordx4 v[104:107], v[4:5], off offset:-2048
	global_load_dwordx4 v[100:103], v[4:5], off
	global_load_dwordx4 v[96:99], v[4:5], off offset:2048
	global_load_dwordx4 v[92:95], v[2:3], off offset:-4096
	global_load_dwordx4 v[88:91], v[2:3], off offset:-2048
	global_load_dwordx4 v[84:87], v[2:3], off
	global_load_dwordx4 v[80:83], v[2:3], off offset:2048
	ds_read_b128 v[128:131], v169
	ds_read_b128 v[10:13], v169 offset:32
	ds_read_b128 v[6:9], v169 offset:64
	ds_read_b128 v[2:5], v169 offset:96
	s_cmp_lt_i32 s6, 0
	s_cselect_b64 s[0:1], -1, 0
	s_cmp_gt_i32 s6, -1
	s_cselect_b64 s[2:3], -1, 0
	s_cmp_lg_u32 s6, s22
	s_cselect_b64 s[6:7], -1, 0
	s_and_b64 s[6:7], s[2:3], s[6:7]
	s_mov_b64 s[18:19], -1
	s_and_b64 vcc, exec, s[6:7]
	v_mbcnt_hi_u32_b32 v1, -1, v195
	s_mov_b64 s[6:7], -1
	s_cbranch_vccz .LBB0_653
	s_waitcnt lgkmcnt(3)
	v_mfma_f32_32x32x16_bf16 v[48:63], v[128:131], v[112:115], 0
	s_mov_b64 s[6:7], 0
	s_waitcnt lgkmcnt(2)
	v_mfma_f32_32x32x16_bf16 v[48:63], v[10:13], v[116:119], v[48:63]
	s_waitcnt lgkmcnt(1)
	v_mfma_f32_32x32x16_bf16 v[48:63], v[6:9], v[120:123], v[48:63]
	s_waitcnt lgkmcnt(0)
	v_mfma_f32_32x32x16_bf16 v[48:63], v[2:5], v[124:127], v[48:63]
	s_nop 11
	v_exp_f32_e32 v14, v48
	v_exp_f32_e32 v15, v49
	v_exp_f32_e32 v48, v50
	v_exp_f32_e32 v49, v51
	v_exp_f32_e32 v50, v52
	v_exp_f32_e32 v51, v53
	v_exp_f32_e32 v52, v54
	v_exp_f32_e32 v53, v55
	v_exp_f32_e32 v54, v56
	v_exp_f32_e32 v55, v57
	v_exp_f32_e32 v56, v58
	v_exp_f32_e32 v57, v59
	v_exp_f32_e32 v58, v60
	v_exp_f32_e32 v59, v61
	v_exp_f32_e32 v60, v62
	v_exp_f32_e32 v61, v63
	v_pk_add_f32 v[14:15], v[14:15], 1.0 op_sel_hi:[1,0]
	v_pk_add_f32 v[48:49], v[48:49], 1.0 op_sel_hi:[1,0]
	v_pk_add_f32 v[58:59], v[58:59], 1.0 op_sel_hi:[1,0]
	v_pk_add_f32 v[50:51], v[50:51], 1.0 op_sel_hi:[1,0]
	v_pk_add_f32 v[52:53], v[52:53], 1.0 op_sel_hi:[1,0]
	v_rcp_f32_e32 v14, v14
	v_rcp_f32_e32 v15, v15
	v_rcp_f32_e32 v48, v48
	v_rcp_f32_e32 v49, v49
	v_rcp_f32_e32 v192, v58
	v_rcp_f32_e32 v193, v59
	v_pk_add_f32 v[58:59], v[60:61], 1.0 op_sel_hi:[1,0]
	v_pk_add_f32 v[54:55], v[54:55], 1.0 op_sel_hi:[1,0]
	v_pk_add_f32 v[56:57], v[56:57], 1.0 op_sel_hi:[1,0]
	v_rcp_f32_e32 v50, v50
	v_rcp_f32_e32 v51, v51
	v_rcp_f32_e32 v52, v52
	v_rcp_f32_e32 v53, v53
	v_rcp_f32_e32 v205, v59
	v_rcp_f32_e32 v68, v54
	v_rcp_f32_e32 v69, v55
	v_rcp_f32_e32 v70, v56
	v_rcp_f32_e32 v71, v57
	v_rcp_f32_e32 v204, v58
	v_pk_add_f32 v[54:55], v[14:15], 1.0 op_sel_hi:[1,0] neg_lo:[1,0] neg_hi:[1,0]
	v_pk_add_f32 v[56:57], v[48:49], 1.0 op_sel_hi:[1,0] neg_lo:[1,0] neg_hi:[1,0]
	v_pk_add_f32 v[62:63], v[50:51], 1.0 op_sel_hi:[1,0] neg_lo:[1,0] neg_hi:[1,0]
	v_pk_add_f32 v[64:65], v[52:53], 1.0 op_sel_hi:[1,0] neg_lo:[1,0] neg_hi:[1,0]
	v_pk_mul_f32 v[58:59], v[54:55], v[56:57]
	v_pk_add_f32 v[72:73], v[68:69], 1.0 op_sel_hi:[1,0] neg_lo:[1,0] neg_hi:[1,0]
	v_pk_add_f32 v[74:75], v[70:71], 1.0 op_sel_hi:[1,0] neg_lo:[1,0] neg_hi:[1,0]
	v_mul_f32_e32 v214, v58, v59
	v_pk_mul_f32 v[58:59], v[62:63], v[64:65]
	v_pk_add_f32 v[206:207], v[192:193], 1.0 op_sel_hi:[1,0] neg_lo:[1,0] neg_hi:[1,0]
	v_pk_add_f32 v[76:77], v[204:205], 1.0 op_sel_hi:[1,0] neg_lo:[1,0] neg_hi:[1,0]
	v_mul_f32_e32 v54, v58, v59
	v_pk_mul_f32 v[58:59], v[72:73], v[74:75]
	v_mov_b32_e32 v67, v54
	v_mul_f32_e32 v62, v58, v59
	v_pk_mul_f32 v[58:59], v[206:207], v[76:77]
	v_mov_b32_e32 v61, v62
	v_mul_f32_e32 v58, v58, v59
	v_mov_b32_e32 v59, v58
	v_mov_b32_e32 v215, v214
	v_permlane32_swap_b32_e32 v67, v54
	v_permlane32_swap_b32_e32 v61, v62
	v_permlane32_swap_b32_e32 v58, v59
	v_permlane32_swap_b32_e32 v214, v215
	s_nop 1
	v_mul_f32_e32 v58, v58, v59
	v_mul_f32_e32 v62, v62, v58
	v_mul_f32_e32 v61, v61, v62
	v_mul_f32_e32 v54, v54, v61
	v_mov_b32_e32 v60, v215
	v_mul_f32_e32 v66, v67, v54
	v_mul_f32_e32 v206, v60, v66
	v_cndmask_b32_e64 v60, v66, v206, s[4:5]
	v_cndmask_b32_e64 v72, 1.0, v59, s[4:5]
	v_mul_f32_e32 v59, v139, v60
	v_cndmask_b32_e64 v54, v61, v54, s[4:5]
	v_cndmask_b32_e64 v61, v58, v62, s[4:5]
	v_mul_f32_e32 v58, v57, v59
	v_mul_f32_e32 v57, v56, v58
	v_mul_f32_e32 v56, v55, v57
	v_mul_f32_e32 v55, v139, v54
	v_mul_f32_e32 v54, v65, v55
	v_pk_mul_f32 v[14:15], v[14:15], v[56:57]
	v_mul_f32_e32 v57, v64, v54
	v_mul_f32_e32 v79, v139, v61
	v_mul_f32_e32 v56, v63, v57
	v_mul_f32_e32 v78, v75, v79
	v_pk_mul_f32 v[48:49], v[48:49], v[58:59]
	v_pk_mul_f32 v[50:51], v[50:51], v[56:57]
	v_pk_mul_f32 v[52:53], v[52:53], v[54:55]
	v_cvt_pk_bf16_f32 v200, v14, v15
	v_mul_f32_e32 v15, v74, v78
	v_mul_f32_e32 v211, v139, v72
	ds_read_b64_tr_b16 v[64:65], v141
	ds_read_b64_tr_b16 v[66:67], v141 offset:1536
	ds_read_b64_tr_b16 v[188:189], v141 offset:3072
	ds_read_b64_tr_b16 v[190:191], v141 offset:4608
	ds_read_b64_tr_b16 v[196:197], v141 offset:64
	ds_read_b64_tr_b16 v[198:199], v141 offset:1600
	ds_read_b64_tr_b16 v[184:185], v141 offset:3136
	ds_read_b64_tr_b16 v[186:187], v141 offset:4672
	s_waitcnt lgkmcnt(0)
	v_cvt_pk_bf16_f32 v201, v48, v49
	v_cvt_pk_bf16_f32 v202, v50, v51
	v_cvt_pk_bf16_f32 v203, v52, v53
	v_mul_f32_e32 v14, v73, v15
	v_mul_f32_e32 v210, v211, v77
	v_mfma_f32_32x32x16_bf16 v[48:63], v[64:67], v[200:203], v[32:47]
	v_mul_f32_e64 v14, v68, v14
	v_mul_f32_e64 v15, v69, v15
	v_mul_f32_e64 v208, v70, v78
	v_mul_f32_e64 v209, v71, v79
	v_mul_f32_e32 v213, v76, v210
	v_mul_f32_e32 v212, v207, v213
	v_pk_mul_f32 v[192:193], v[192:193], v[212:213]
	v_mfma_f32_32x32x16_bf16 v[64:79], v[196:199], v[200:203], v[16:31]
	v_cvt_pk_bf16_f32 v196, v14, v15
	v_mov_b32_e32 v14, v214
	v_mul_f32_e32 v14, v14, v206
	v_mul_f32_e32 v14, v139, v14
	v_mul_f32_e64 v200, v204, v210
	v_mul_f32_e64 v201, v205, v211
	v_cmp_gt_f32_e32 vcc, s21, v14
	v_cvt_pk_bf16_f32 v197, v208, v209
	v_cvt_pk_bf16_f32 v198, v192, v193
	v_cvt_pk_bf16_f32 v199, v200, v201
	s_cmp_eq_u64 vcc, exec
	s_cselect_b64 s[18:19], -1, 0
	v_mfma_f32_32x32x16_bf16 v[48:63], v[188:191], v[196:199], v[48:63]
	v_mfma_f32_32x32x16_bf16 v[64:79], v[184:187], v[196:199], v[64:79]
.LBB0_653:
	s_andn2_b64 vcc, exec, s[6:7]
	s_cbranch_vccnz .LBB0_650
	s_waitcnt lgkmcnt(3)
	v_mfma_f32_32x32x16_bf16 v[48:63], v[128:131], v[112:115], 0
	s_nop 7
	v_cndmask_b32_e64 v68, v133, 16, s[0:1]
	v_cmp_lt_u32_e32 vcc, v132, v68
	v_cmp_lt_u32_e64 s[10:11], v143, v68
	v_cmp_lt_u32_e64 s[0:1], v145, v68
	s_or_b64 vcc, s[10:11], vcc
	v_cmp_lt_u32_e64 s[6:7], v149, v68
	s_waitcnt lgkmcnt(2)
	v_mfma_f32_32x32x16_bf16 v[48:63], v[10:13], v[116:119], v[48:63]
	s_waitcnt lgkmcnt(1)
	v_mfma_f32_32x32x16_bf16 v[48:63], v[6:9], v[120:123], v[48:63]
	s_waitcnt lgkmcnt(0)
	v_mfma_f32_32x32x16_bf16 v[48:63], v[2:5], v[124:127], v[48:63]
	s_nop 11
	v_exp_f32_e32 v2, v48
	v_exp_f32_e32 v3, v49
	v_exp_f32_e32 v4, v50
	v_exp_f32_e32 v5, v51
	v_exp_f32_e32 v6, v52
	v_exp_f32_e32 v7, v53
	v_pk_add_f32 v[2:3], v[2:3], 1.0 op_sel_hi:[1,0]
	v_exp_f32_e32 v8, v54
	v_exp_f32_e32 v9, v55
	v_pk_add_f32 v[4:5], v[4:5], 1.0 op_sel_hi:[1,0]
	v_rcp_f32_e32 v2, v2
	v_rcp_f32_e32 v3, v3
	v_rcp_f32_e32 v4, v4
	v_rcp_f32_e32 v5, v5
	v_pk_add_f32 v[6:7], v[6:7], 1.0 op_sel_hi:[1,0]
	v_exp_f32_e32 v50, v56
	v_exp_f32_e32 v51, v57
	v_rcp_f32_e32 v6, v6
	v_rcp_f32_e32 v7, v7
	v_pk_add_f32 v[8:9], v[8:9], 1.0 op_sel_hi:[1,0]
	v_pk_add_f32 v[10:11], v[2:3], 1.0 op_sel_hi:[1,0] neg_lo:[1,0] neg_hi:[1,0]
	v_rcp_f32_e32 v8, v8
	v_pk_add_f32 v[12:13], v[4:5], 1.0 op_sel_hi:[1,0] neg_lo:[1,0] neg_hi:[1,0]
	v_cndmask_b32_e64 v11, 1.0, v11, s[10:11]
	v_cndmask_b32_e64 v49, 0, v3, s[10:11]
	v_cmp_lt_u32_e64 s[10:11], v147, v68
	v_rcp_f32_e32 v9, v9
	v_exp_f32_e32 v54, v58
	v_exp_f32_e32 v55, v59
	v_cndmask_b32_e64 v13, 1.0, v13, s[10:11]
	s_or_b64 s[0:1], s[10:11], s[0:1]
	v_cndmask_b32_e64 v5, 0, v5, s[10:11]
	v_cmp_lt_u32_e64 s[10:11], v151, v68
	v_pk_add_f32 v[50:51], v[50:51], 1.0 op_sel_hi:[1,0]
	v_pk_add_f32 v[14:15], v[6:7], 1.0 op_sel_hi:[1,0] neg_lo:[1,0] neg_hi:[1,0]
	v_cndmask_b32_e32 v10, 1.0, v10, vcc
	v_cndmask_b32_e32 v48, 0, v2, vcc
	s_or_b64 vcc, s[10:11], s[6:7]
	v_rcp_f32_e32 v50, v50
	v_rcp_f32_e32 v51, v51
	v_cndmask_b32_e64 v12, 1.0, v12, s[0:1]
	v_cndmask_b32_e64 v4, 0, v4, s[0:1]
	v_cndmask_b32_e32 v14, 1.0, v14, vcc
	v_cndmask_b32_e32 v6, 0, v6, vcc
	v_cmp_lt_u32_e32 vcc, v153, v68
	v_cmp_lt_u32_e64 s[0:1], v155, v68
	v_pk_add_f32 v[2:3], v[8:9], 1.0 op_sel_hi:[1,0] neg_lo:[1,0] neg_hi:[1,0]
	s_or_b64 vcc, s[0:1], vcc
	v_pk_add_f32 v[54:55], v[54:55], 1.0 op_sel_hi:[1,0]
	v_cndmask_b32_e64 v53, 1.0, v3, s[0:1]
	v_cndmask_b32_e32 v52, 1.0, v2, vcc
	v_cndmask_b32_e32 v8, 0, v8, vcc
	v_cndmask_b32_e64 v9, 0, v9, s[0:1]
	v_cmp_lt_u32_e32 vcc, v159, v68
	v_cmp_lt_u32_e64 s[0:1], v160, v68
	v_rcp_f32_e32 v54, v54
	v_rcp_f32_e32 v55, v55
	v_pk_add_f32 v[2:3], v[50:51], 1.0 op_sel_hi:[1,0] neg_lo:[1,0] neg_hi:[1,0]
	s_or_b64 vcc, s[0:1], vcc
	v_cndmask_b32_e64 v57, 1.0, v3, s[0:1]
	v_cndmask_b32_e32 v56, 1.0, v2, vcc
	v_cndmask_b32_e32 v58, 0, v50, vcc
	v_cndmask_b32_e64 v59, 0, v51, s[0:1]
	v_cmp_lt_u32_e32 vcc, v161, v68
	v_cmp_lt_u32_e64 s[0:1], v162, v68
	v_exp_f32_e32 v50, v60
	v_exp_f32_e32 v51, v61
	s_or_b64 vcc, s[0:1], vcc
	v_pk_add_f32 v[2:3], v[54:55], 1.0 op_sel_hi:[1,0] neg_lo:[1,0] neg_hi:[1,0]
	v_cndmask_b32_e32 v64, 0, v54, vcc
	v_cndmask_b32_e64 v65, 0, v55, s[0:1]
	v_exp_f32_e32 v54, v62
	v_exp_f32_e32 v55, v63
	v_pk_add_f32 v[50:51], v[50:51], 1.0 op_sel_hi:[1,0]
	v_cndmask_b32_e64 v61, 1.0, v3, s[0:1]
	v_rcp_f32_e32 v50, v50
	v_rcp_f32_e32 v51, v51
	v_pk_add_f32 v[54:55], v[54:55], 1.0 op_sel_hi:[1,0]
	v_cndmask_b32_e32 v60, 1.0, v2, vcc
	v_rcp_f32_e32 v54, v54
	v_rcp_f32_e32 v55, v55
	v_cmp_lt_u32_e32 vcc, v163, v68
	v_cmp_lt_u32_e64 s[0:1], v164, v68
	v_pk_add_f32 v[2:3], v[50:51], 1.0 op_sel_hi:[1,0] neg_lo:[1,0] neg_hi:[1,0]
	s_or_b64 vcc, s[0:1], vcc
	v_cndmask_b32_e64 v63, 1.0, v3, s[0:1]
	v_cndmask_b32_e32 v62, 1.0, v2, vcc
	v_cndmask_b32_e32 v66, 0, v50, vcc
	v_cndmask_b32_e64 v67, 0, v51, s[0:1]
	v_pk_add_f32 v[2:3], v[54:55], 1.0 op_sel_hi:[1,0] neg_lo:[1,0] neg_hi:[1,0]
	v_cmp_lt_u32_e32 vcc, v165, v68
	v_cmp_lt_u32_e64 s[0:1], v166, v68
	s_or_b64 vcc, s[0:1], vcc
	v_cndmask_b32_e32 v68, 1.0, v2, vcc
	v_cndmask_b32_e64 v69, 1.0, v3, s[0:1]
	v_cndmask_b32_e64 v15, 1.0, v15, s[10:11]
	v_cndmask_b32_e32 v70, 0, v54, vcc
	v_pk_mul_f32 v[50:51], v[14:15], v[52:53]
	v_cndmask_b32_e64 v71, 0, v55, s[0:1]
	v_pk_mul_f32 v[2:3], v[10:11], v[12:13]
	s_nop 0
	v_mul_f32_e32 v1, v2, v3
	v_mul_f32_e32 v3, v50, v51
	v_pk_mul_f32 v[50:51], v[56:57], v[60:61]
	v_mov_b32_e32 v56, v3
	v_mul_f32_e32 v14, v50, v51
	v_pk_mul_f32 v[50:51], v[62:63], v[68:69]
	v_mov_b32_e32 v10, v14
	v_mul_f32_e32 v50, v50, v51
	v_mov_b32_e32 v51, v50
	v_mov_b32_e32 v2, v1
	v_permlane32_swap_b32_e32 v56, v3
	v_permlane32_swap_b32_e32 v10, v14
	v_permlane32_swap_b32_e32 v50, v51
	v_permlane32_swap_b32_e32 v1, v2
	s_nop 1
	v_mul_f32_e32 v50, v50, v51
	v_mul_f32_e32 v14, v14, v50
	v_mul_f32_e32 v10, v10, v14
	v_mul_f32_e32 v55, v3, v10
	v_mov_b32_e32 v54, v2
	v_mul_f32_e32 v56, v56, v55
	v_mul_f32_e32 v3, v54, v56
	v_cndmask_b32_e64 v54, v56, v3, s[4:5]
	v_cndmask_b32_e64 v56, 1.0, v51, s[4:5]
	v_mul_f32_e32 v51, v139, v54
	v_cndmask_b32_e64 v10, v10, v55, s[4:5]
	v_cndmask_b32_e64 v14, v50, v14, s[4:5]
	v_mul_f32_e32 v50, v13, v51
	v_pk_mul_f32 v[72:73], v[4:5], v[50:51]
	v_mul_f32_e32 v5, v139, v10
	v_mul_f32_e32 v13, v12, v50
	v_mul_f32_e32 v4, v53, v5
	v_mul_f32_e32 v12, v11, v13
	v_mul_f32_e32 v11, v52, v4
	v_cndmask_b32_e64 v7, 0, v7, s[10:11]
	v_mul_f32_e32 v10, v15, v11
	v_pk_mul_f32 v[54:55], v[48:49], v[12:13]
	v_pk_mul_f32 v[74:75], v[6:7], v[10:11]
	v_pk_mul_f32 v[76:77], v[8:9], v[4:5]
	v_cvt_pk_bf16_f32 v52, v54, v55
	v_cvt_pk_bf16_f32 v53, v72, v73
	v_cvt_pk_bf16_f32 v54, v74, v75
	v_cvt_pk_bf16_f32 v55, v76, v77
	v_mul_f32_e32 v79, v139, v14
	ds_read_b64_tr_b16 v[48:49], v141
	ds_read_b64_tr_b16 v[50:51], v141 offset:1536
	ds_read_b64_tr_b16 v[8:9], v141 offset:3072
	ds_read_b64_tr_b16 v[10:11], v141 offset:4608
	ds_read_b64_tr_b16 v[12:13], v141 offset:64
	ds_read_b64_tr_b16 v[14:15], v141 offset:1600
	ds_read_b64_tr_b16 v[4:5], v141 offset:3136
	ds_read_b64_tr_b16 v[6:7], v141 offset:4672
	s_waitcnt lgkmcnt(0)
	v_mul_f32_e32 v78, v61, v79
	v_mfma_f32_32x32x16_bf16 v[32:47], v[48:51], v[52:55], v[32:47]
	v_mul_f32_e32 v61, v60, v78
	v_mul_f32_e32 v60, v57, v61
	v_mul_f32_e32 v57, v139, v56
	v_mul_f32_e32 v56, v57, v69
	v_mul_f32_e64 v48, v58, v60
	v_mul_f32_e64 v49, v59, v61
	v_mul_f32_e32 v59, v68, v56
	v_mul_f32_e32 v58, v63, v59
	v_mfma_f32_32x32x16_bf16 v[16:31], v[12:15], v[52:55], v[16:31]
	v_mul_f32_e64 v50, v64, v78
	v_mul_f32_e64 v51, v65, v79
	v_mul_f32_e64 v14, v66, v58
	v_mul_f32_e64 v15, v67, v59
	v_mul_f32_e64 v52, v70, v56
	v_mul_f32_e64 v53, v71, v57
	v_cvt_pk_bf16_f32 v12, v48, v49
	v_cvt_pk_bf16_f32 v13, v50, v51
	v_cvt_pk_bf16_f32 v14, v14, v15
	v_cvt_pk_bf16_f32 v15, v52, v53
	v_mov_b64_e32 v[62:63], v[46:47]
	s_nop 0
	v_mov_b64_e32 v[78:79], v[30:31]
	v_mov_b64_e32 v[60:61], v[44:45]
	v_mov_b64_e32 v[58:59], v[42:43]
	v_mov_b64_e32 v[56:57], v[40:41]
	v_mov_b64_e32 v[54:55], v[38:39]
	v_mov_b64_e32 v[52:53], v[36:37]
	v_mov_b64_e32 v[50:51], v[34:35]
	v_mov_b64_e32 v[48:49], v[32:33]
	v_mov_b64_e32 v[76:77], v[28:29]
	v_mov_b64_e32 v[74:75], v[26:27]
	v_mov_b64_e32 v[72:73], v[24:25]
	v_mov_b64_e32 v[70:71], v[22:23]
	v_mov_b64_e32 v[68:69], v[20:21]
	v_mov_b64_e32 v[66:67], v[18:19]
	v_mov_b64_e32 v[64:65], v[16:17]
	v_mfma_f32_32x32x16_bf16 v[48:63], v[8:11], v[12:15], v[48:63]
	s_and_b64 vcc, exec, s[2:3]
	v_mfma_f32_32x32x16_bf16 v[64:79], v[4:7], v[12:15], v[64:79]
	s_cbranch_vccz .LBB0_650
	v_mul_f32_e32 v1, v1, v3
	v_mul_f32_e32 v14, v139, v1
	v_cmp_gt_f32_e32 vcc, s21, v14
	s_cmp_eq_u64 vcc, exec
	s_cselect_b64 s[18:19], -1, 0
	s_branch .LBB0_650
